# mirrored variant: static s_setprio 1 for waves 0-3 (older half) during the attention phase
# baseline (speedup 1.0000x reference)
; DI int otid() { int t = threadIdx.x; asm volatile("" : "+v"(t)); return t; }
; DI void phase_attn(const Params& p, int layer, char* smem) {
;   unsigned* ctr = (unsigned*)(p.ws + OFF_CTRL) + layer * 8;
;   int qsel = 0;
;   int* s_item = (int*)(smem + A_BIAS + 8192);
;   float* sbias = (float*)(smem + A_BIAS);
;   const bf16_t* big = (const bf16_t*)(p.ws + OFF_BIG);
;   bf16_t* ocat = (bf16_t*)(p.ws + OFF_OCAT);
;   NaInfo na0; na0.r0q = 0; na0.c0 = 0; na0.rq = 0; na0.cq = 0; na0.sb = sbias;
;   for (;;) {
;     const int tid = otid(), lane = tid & 63, wave = tid >> 6, r = lane & 31, h = lane >> 5;
;     __syncthreads();
;     const int xq = (blockIdx.x + qsel) & 7;
;     if (tid == 0) *s_item = (int)atomicAdd(ctr + xq, 1u);
;     __syncthreads();
;     const int it = *s_item;
;     if (it >= N_ITEMS_XCD) { if (++qsel >= 8) break; continue; }
.LBB0_104:
	s_andn2_b64 vcc, exec, s[0:1]
	s_cbranch_vccnz .LBB0_407
	s_and_b32 s0, s46, -8
	s_ashr_i32 s1, s0, 31
	s_lshl_b64 s[0:1], s[0:1], 2
	s_add_u32 s0, s86, s0
	s_addc_u32 s1, s87, s1
	v_writelane_b32 v255, s0, 4
	s_nop 1
	v_writelane_b32 v255, s1, 5
	s_nop 0
	v_readlane_b32 s0, v255, 1
	s_mov_b32 s2, s0
	s_mul_i32 s53, s0, 0x744
	s_lshl_b32 s0, s0, 9
	v_readlane_b32 s1, v255, 2
	v_writelane_b32 v255, s0, 6
	s_or_b32 s0, s0, 10
	v_writelane_b32 v255, s0, 7
	s_lshl_b32 s0, s2, 1
	s_lshl_b32 s4, s2, 2
	s_ashr_i32 s1, s0, 31
	s_lshl_b32 s2, s2, 6
	s_ashr_i32 s3, s2, 31
	s_lshl_b64 s[0:1], s[0:1], 2
	s_add_u32 s0, s86, s0
	s_addc_u32 s1, s87, s1
	v_writelane_b32 v255, s0, 8
	s_mov_b32 s56, s53
	s_nop 0
	v_writelane_b32 v255, s1, 9
	s_lshl_b64 s[0:1], s[2:3], 2
	s_waitcnt lgkmcnt(0)
	s_add_u32 s0, s18, s0
	s_addc_u32 s1, s19, s1
	v_writelane_b32 v255, s0, 10
	s_nop 1
	v_writelane_b32 v255, s1, 11
	v_writelane_b32 v255, s4, 12
	s_ashr_i32 s0, s4, 31
	v_writelane_b32 v255, s0, 13
	s_ashr_i32 s1, s53, 31
	s_mov_b32 s0, s53
	v_writelane_b32 v255, s0, 14
	s_nop 1
	v_writelane_b32 v255, s1, 15
	s_mov_b32 s0, 0
	v_writelane_b32 v255, s0, 16
	v_writelane_b32 v255, s53, 17
	v_writelane_b32 v255, s56, 18
	v_readfirstlane_b32 s98, v228
	s_nop 0
	s_cmpk_lt_u32 s98, 0x100
	s_cbranch_scc0 .Lattn_prio_done
	s_setprio 1
